# static s_setprio 1 for waves 4-7 in the mixer phases (att/retA/hgA and retB/hgB), reset at phase end
# speedup vs baseline: 1.0062x; 1.0034x over previous
.LBB0_15:
	s_setprio 0
	v_readlane_b32 s2, v255, 48
	s_cmp_eq_u32 s2, 0
	s_cbranch_scc1 .Lsq_std
	s_mov_b32 s3, 0x48240
	s_bitcmp1_b32 s3, s80
	s_cbranch_scc0 .Lsq_inN
	s_add_i32 s80, s80, 1
	s_mov_b64 s[0:1], -1
	s_branch .LBB0_423

.LBB0_180:
	s_andn2_b64 vcc, exec, s[0:1]
	s_cbranch_vccnz .LBB0_203
	v_readlane_b32 s0, v253, 27
	v_mov_b32_e32 v24, v200
	v_readlane_b32 s1, v253, 28
	s_andn2_b64 vcc, exec, s[0:1]
	v_readfirstlane_b32 s2, v24
	s_cbranch_vccnz .LBB0_188
	s_lshr_b32 vcc_lo, s2, 6
	s_cmp_ge_u32 vcc_lo, 4
	s_cbranch_scc0 .Lprio_s4
	s_setprio 1
.Lprio_s4:
	v_readlane_b32 s6, v253, 30
	v_ashrrev_i32_e32 v112, 2, v24
	v_readlane_b32 s7, v253, 31
	s_waitcnt vmcnt(0)
	v_add_u32_e32 v0, s88, v112
	v_lshlrev_b32_e32 v31, 3, v24
	v_mov_b64_e32 v[26:27], s[6:7]
	v_mad_i64_i32 v[0:1], s[6:7], v0, s93, v[26:27]
	v_and_b32_e32 v76, 0xffffffc0, v31
	v_ashrrev_i32_e32 v77, 31, v76
	v_readlane_b32 s6, v253, 34
	v_lshlrev_b64 v[16:17], 1, v[76:77]
	v_readlane_b32 s7, v253, 35
	v_and_b32_e32 v30, 56, v31
	v_lshlrev_b32_e32 v32, 1, v30
	v_lshl_add_u64 v[18:19], s[6:7], 0, v[16:17]
	v_readlane_b32 s6, v253, 36
	v_readlane_b32 s7, v253, 37
	v_mov_b32_e32 v33, v129
	v_lshl_add_u64 v[18:19], v[18:19], 0, v[32:33]
	v_lshl_add_u64 v[16:17], s[6:7], 0, v[16:17]
	v_lshl_add_u64 v[20:21], v[16:17], 0, v[32:33]
	v_and_b32_e32 v33, -16, v112
	v_and_b32_e32 v25, 15, v24
	v_lshlrev_b32_e32 v2, 4, v24
	v_add_u32_e32 v33, s88, v33
	v_and_b32_e32 v28, 48, v2
	v_or_b32_e32 v33, v33, v25
	v_lshlrev_b32_e32 v128, 1, v28
	v_mad_i64_i32 v[26:27], s[6:7], v33, s93, v[26:27]
	v_lshrrev_b32_e32 v33, 1, v24
	v_lshl_add_u64 v[12:13], v[0:1], 0, v[128:129]
	v_and_b32_e32 v34, 24, v33
	global_load_dwordx4 v[0:3], v[12:13], off offset:3088
	global_load_dwordx4 v[4:7], v[12:13], off offset:3072
	global_load_dwordx4 v[8:11], v[12:13], off offset:3856
	s_nop 0
	global_load_dwordx4 v[12:15], v[12:13], off offset:3840
	v_lshlrev_b32_e32 v36, 1, v34
	v_mov_b32_e32 v37, v129
	v_lshl_add_u64 v[26:27], v[26:27], 0, v[36:37]
	global_load_dwordx4 v[16:19], v[18:19], off
	s_nop 0
	global_load_dwordx4 v[20:23], v[20:21], off
	s_nop 0
	global_load_dwordx4 v[68:71], v[26:27], off offset:2304
	global_load_dwordx4 v[64:67], v[26:27], off offset:2368
	v_readlane_b32 s0, v255, 31
	v_readlane_b32 s1, v255, 32
	s_mulk_i32 s0, 0x180
	s_ashr_i32 s1, s0, 31
	v_readlane_b32 s40, v254, 61
	s_lshl_b64 s[0:1], s[0:1], 2
	v_readlane_b32 s52, v255, 9
	v_readlane_b32 s53, v255, 10
	s_add_u32 s0, s52, s0
	v_lshrrev_b32_e32 v26, 3, v24
	s_movk_i32 s3, 0x90
	s_addc_u32 s1, s53, s1
	v_bfe_u32 v29, v24, 4, 2
	v_mul_lo_u32 v26, v26, s3
	s_ashr_i32 s2, s2, 2
	v_add3_u32 v115, 16, v32, v26
	v_bfi_b32 v116, -16, s2, v24
	v_lshlrev_b32_e32 v26, 2, v29
	v_sub_u32_e32 v32, v116, v26
	v_sub_u32_e32 v33, 0, v32
	v_max_i32_e32 v33, v32, v33
	v_cvt_f32_u32_e32 v121, v33
	v_xad_u32 v33, v26, -1, v116
	v_sub_u32_e32 v35, 0, v33
	v_max_i32_e32 v33, v33, v35
	v_cvt_f32_u32_e32 v122, v33
	v_add_u32_e32 v33, -2, v32
	v_sub_u32_e32 v35, 2, v32
	v_max_i32_e32 v33, v33, v35
	v_cvt_f32_u32_e32 v123, v33
	v_add_u32_e32 v33, -3, v32
	v_sub_u32_e32 v35, 3, v32
	v_max_i32_e32 v33, v33, v35
	v_cvt_f32_u32_e32 v124, v33
	v_add_u32_e32 v33, -16, v32
	v_sub_u32_e32 v35, 16, v32
	v_max_i32_e32 v33, v33, v35
	v_cvt_f32_u32_e32 v125, v33
	v_subrev_u32_e32 v33, 17, v32
	v_sub_u32_e32 v35, 17, v32
	v_max_i32_e32 v33, v33, v35
	v_cvt_f32_u32_e32 v126, v33
	v_subrev_u32_e32 v33, 18, v32
	v_sub_u32_e32 v35, 18, v32
	v_max_i32_e32 v33, v33, v35
	v_cvt_f32_u32_e32 v127, v33
	v_subrev_u32_e32 v33, 19, v32
	v_sub_u32_e32 v35, 19, v32
	v_max_i32_e32 v33, v33, v35
	v_cvt_f32_u32_e32 v135, v33
	v_subrev_u32_e32 v33, 32, v32
	v_sub_u32_e32 v35, 32, v32
	v_max_i32_e32 v33, v33, v35
	v_cvt_f32_u32_e32 v137, v33
	v_subrev_u32_e32 v33, 33, v32
	v_sub_u32_e32 v35, 33, v32
	v_max_i32_e32 v33, v33, v35
	v_cvt_f32_u32_e32 v140, v33
	v_subrev_u32_e32 v33, 34, v32
	v_sub_u32_e32 v35, 34, v32
	v_max_i32_e32 v33, v33, v35
	v_cvt_f32_u32_e32 v141, v33
	v_subrev_u32_e32 v33, 35, v32
	v_sub_u32_e32 v35, 35, v32
	v_max_i32_e32 v33, v33, v35
	v_cvt_f32_u32_e32 v142, v33
	v_subrev_u32_e32 v33, 48, v32
	v_sub_u32_e32 v35, 48, v32
	v_max_i32_e32 v33, v33, v35
	v_cvt_f32_u32_e32 v143, v33
	v_subrev_u32_e32 v33, 49, v32
	v_sub_u32_e32 v35, 49, v32
	v_max_i32_e32 v33, v33, v35
	v_cvt_f32_u32_e32 v144, v33
	v_subrev_u32_e32 v33, 50, v32
	v_sub_u32_e32 v35, 50, v32
	v_max_i32_e32 v33, v33, v35
	v_cvt_f32_u32_e32 v145, v33
	v_subrev_u32_e32 v33, 51, v32
	v_sub_u32_e32 v35, 51, v32
	v_max_i32_e32 v33, v33, v35
	v_cvt_f32_u32_e32 v146, v33
	v_subrev_u32_e32 v33, 64, v32
	v_sub_u32_e32 v35, 64, v32
	v_max_i32_e32 v33, v33, v35
	v_cvt_f32_u32_e32 v147, v33
	v_add_u32_e32 v33, 0xffffffbf, v32
	v_sub_u32_e32 v35, 0x41, v32
	v_max_i32_e32 v33, v33, v35
	v_cvt_f32_u32_e32 v148, v33
	v_add_u32_e32 v33, 0xffffffbe, v32
	v_sub_u32_e32 v35, 0x42, v32
	v_max_i32_e32 v33, v33, v35
	v_cvt_f32_u32_e32 v149, v33
	v_add_u32_e32 v33, 0xffffffbd, v32
	v_sub_u32_e32 v35, 0x43, v32
	v_max_i32_e32 v33, v33, v35
	v_cvt_f32_u32_e32 v150, v33
	v_add_u32_e32 v33, 0xffffffb0, v32
	v_sub_u32_e32 v35, 0x50, v32
	v_max_i32_e32 v33, v33, v35
	v_cvt_f32_u32_e32 v151, v33
	v_add_u32_e32 v33, 0xffffffaf, v32
	v_sub_u32_e32 v35, 0x51, v32
	v_max_i32_e32 v33, v33, v35
	v_cvt_f32_u32_e32 v152, v33
	v_add_u32_e32 v33, 0xffffffae, v32
	v_sub_u32_e32 v35, 0x52, v32
	v_max_i32_e32 v33, v33, v35
	v_cvt_f32_u32_e32 v153, v33
	v_add_u32_e32 v33, 0xffffffad, v32
	v_sub_u32_e32 v35, 0x53, v32
	v_max_i32_e32 v33, v33, v35
	v_cvt_f32_u32_e32 v154, v33
	v_add_u32_e32 v33, 0xffffffa0, v32
	v_sub_u32_e32 v35, 0x60, v32
	v_max_i32_e32 v33, v33, v35
	v_cvt_f32_u32_e32 v155, v33
	v_add_u32_e32 v33, 0xffffff9f, v32
	v_sub_u32_e32 v35, 0x61, v32
	v_max_i32_e32 v33, v33, v35
	v_cvt_f32_u32_e32 v156, v33
	v_add_u32_e32 v33, 0xffffff9e, v32
	v_sub_u32_e32 v35, 0x62, v32
	v_max_i32_e32 v33, v33, v35
	v_cvt_f32_u32_e32 v157, v33
	v_add_u32_e32 v33, 0xffffff9d, v32
	v_sub_u32_e32 v35, 0x63, v32
	v_max_i32_e32 v33, v33, v35
	v_cvt_f32_u32_e32 v158, v33
	v_add_u32_e32 v33, 0xffffff90, v32
	v_sub_u32_e32 v35, 0x70, v32
	v_max_i32_e32 v33, v33, v35
	v_cvt_f32_u32_e32 v159, v33
	v_add_u32_e32 v33, 0xffffff8f, v32
	v_sub_u32_e32 v35, 0x71, v32
	v_max_i32_e32 v33, v33, v35
	v_cvt_f32_u32_e32 v160, v33
	v_add_u32_e32 v33, 0xffffff8e, v32
	v_sub_u32_e32 v35, 0x72, v32
	v_mul_lo_u32 v27, v112, s3
	v_max_i32_e32 v33, v33, v35
	v_add3_u32 v114, 16, v128, v27
	s_load_dword s12, s[38:39], 0x0
	v_add_u32_e32 v27, 1, v116
	v_cvt_f32_u32_e32 v161, v33
	v_add_u32_e32 v33, 0xffffff8d, v32
	v_sub_u32_e32 v32, 0x73, v32
	v_cvt_f32_i32_e32 v117, v27
	v_sub_u32_e32 v27, 0x80, v116
	v_cmp_lt_i32_e32 vcc, v210, v205
	v_max_i32_e32 v32, v33, v32
	v_bfi_b32 v113, -16, v112, v24
	v_cvt_f32_i32_e32 v118, v27
	v_lshlrev_b32_e32 v128, 4, v29
	v_bfe_u32 v24, v24, 2, 2
	v_and_b32_e32 v29, 24, v31
	v_cndmask_b32_e32 v31, v204, v210, vcc
	v_cmp_lt_i32_e32 vcc, v211, v205
	v_cvt_f32_u32_e32 v162, v32
	v_or_b32_e32 v24, v26, v24
	v_lshlrev_b32_e32 v119, 2, v31
	v_cndmask_b32_e32 v31, v204, v211, vcc
	v_add_u32_e32 v27, 16, v128
	v_add_u32_e32 v29, 16, v29
	v_lshlrev_b32_e32 v120, 2, v31
	v_mul_u32_u24_e32 v31, 0x90, v25
	v_mul_u32_u24_e32 v24, 0x90, v24
	v_mul_u32_u24_e32 v25, 0x48, v25
	v_lshl_add_u32 v163, v25, 1, v27
	v_lshl_add_u64 v[78:79], s[0:1], 0, v[128:129]
	s_waitcnt lgkmcnt(0)
	s_lshl_b32 s13, s12, 7
	v_lshlrev_b32_e32 v80, 1, v28
	v_lshlrev_b32_e32 v82, 1, v30
	v_lshlrev_b32_e32 v84, 1, v34
	v_lshlrev_b32_e32 v128, 1, v26
	v_add_u32_e32 v164, v27, v31
	v_add_u32_e32 v165, v29, v24
	v_readlane_b32 s15, v253, 29
	s_mov_b32 s0, s62
	v_readlane_b32 s41, v254, 62
	v_readlane_b32 s42, v254, 63
	v_readlane_b32 s43, v255, 0
	v_readlane_b32 s44, v255, 1
	v_readlane_b32 s45, v255, 2
	v_readlane_b32 s46, v255, 3
	v_readlane_b32 s47, v255, 4
	v_readlane_b32 s48, v255, 5
	v_readlane_b32 s49, v255, 6
	v_readlane_b32 s50, v255, 7
	v_readlane_b32 s51, v255, 8
	v_readlane_b32 s54, v255, 11
	v_readlane_b32 s55, v255, 12
	s_branch .LBB0_184

.LBB0_248:
	s_or_b64 exec, exec, s[0:1]
	v_readfirstlane_b32 s0, v200
	s_lshr_b32 s0, s0, 6
	s_cmp_ge_u32 s0, 4
	s_cbranch_scc0 .Lprio_att
	s_setprio 1
.Lprio_att:
	v_readlane_b32 s0, v253, 45
	s_add_i32 s0, s16, s0
	s_ashr_i32 s21, s0, 3
	v_readlane_b32 s0, v253, 54
	v_and_b32_e32 v18, 48, v16
	v_mov_b32_e32 v19, v129
	v_readlane_b32 s1, v253, 55
	v_ashrrev_i32_e32 v0, 1, v16
	v_and_b32_e32 v21, 0xffffffe0, v0
	v_lshl_add_u64 v[8:9], s[0:1], 0, v[18:19]
	v_readlane_b32 s0, v253, 52
	v_and_b32_e32 v222, 15, v16
	v_cmp_lt_i32_e32 vcc, v210, v205
	v_add_u32_e32 v0, s0, v21
	v_or_b32_e32 v10, v0, v222
	v_or_b32_e32 v0, 16, v10
	v_lshlrev_b32_e32 v0, s3, v0
	v_lshlrev_b32_e32 v10, s3, v10
	v_add_u32_e32 v0, s12, v0
	v_add_u32_e32 v10, s12, v10
	v_mad_i64_i32 v[4:5], s[0:1], v0, s93, v[8:9]
	v_mad_i64_i32 v[12:13], s[0:1], v10, s93, v[8:9]
	global_load_dwordx4 v[0:3], v[4:5], off offset:64
	s_nop 0
	global_load_dwordx4 v[4:7], v[4:5], off
	s_nop 0
	global_load_dwordx4 v[8:11], v[12:13], off offset:64
	s_nop 0
	global_load_dwordx4 v[12:15], v[12:13], off
	v_or_b32_e32 v223, v21, v222
	v_cndmask_b32_e32 v21, v204, v210, vcc
	v_cmp_lt_i32_e32 vcc, v211, v205
	v_bfe_u32 v17, v16, 4, 2
	v_lshlrev_b32_e32 v224, 2, v21
	v_cndmask_b32_e32 v21, v204, v211, vcc
	v_lshlrev_b32_e32 v112, 2, v17
	v_lshlrev_b32_e32 v225, 2, v21
	v_bfe_u32 v21, v16, 2, 2
	s_ashr_i32 s24, s2, 1
	v_or_b32_e32 v31, v112, v21
	v_lshlrev_b32_e32 v21, 3, v16
	v_add_u32_e32 v20, 16, v128
	s_andn2_b32 s24, s24, 31
	v_and_b32_e32 v21, 24, v21
	s_movk_i32 s2, 0x90
	v_or_b32_e32 v23, 64, v222
	v_lshl_add_u32 v29, v17, 4, 16
	v_cmp_eq_u32_e64 s[40:41], 0, v17
	v_mad_u64_u32 v[114:115], s[0:1], v137, s2, v[20:21]
	v_mad_u64_u32 v[116:117], s[0:1], v220, s2, v[20:21]
	v_mad_u64_u32 v[118:119], s[0:1], v221, s2, v[20:21]
	v_or_b32_e32 v17, s24, v222
	v_mul_lo_u32 v33, v17, s2
	v_sub_u32_e32 v17, v23, v112
	s_movk_i32 s0, 0x41
	v_add_u32_e32 v22, 16, v21
	v_cvt_f32_ubyte0_e32 v121, v17
	v_cmp_gt_u32_e64 s[42:43], s0, v17
	v_not_b32_e32 v17, v112
	v_or_b32_e32 v21, 2, v112
	v_add_u32_e32 v20, v23, v17
	v_sub_u32_e32 v21, v23, v21
	v_sub_u32_e32 v35, v222, v112
	v_cvt_f32_ubyte0_e32 v123, v20
	v_cmp_gt_u32_e64 s[44:45], s0, v20
	v_or_b32_e32 v20, 3, v112
	v_cvt_f32_ubyte0_e32 v124, v21
	v_cmp_gt_u32_e64 s[48:49], s0, v21
	v_add_u32_e32 v21, 47, v35
	v_sub_u32_e32 v20, v23, v20
	v_cvt_f32_u32_e32 v127, v21
	v_add_u32_e32 v21, 45, v35
	v_cvt_f32_ubyte0_e32 v125, v20
	v_cmp_gt_u32_e64 s[46:47], s0, v20
	v_add_u32_e32 v20, 48, v35
	v_cvt_f32_u32_e32 v141, v21
	v_add_u32_e32 v21, 31, v35
	v_cvt_f32_u32_e32 v126, v20
	v_add_u32_e32 v20, 46, v35
	v_cvt_f32_u32_e32 v143, v21
	v_add_u32_e32 v21, 29, v35
	v_cvt_f32_u32_e32 v140, v20
	v_add_u32_e32 v20, 32, v35
	v_cvt_f32_u32_e32 v145, v21
	v_add_u32_e32 v21, 15, v35
	v_subrev_u32_e32 v27, 49, v35
	v_cvt_f32_u32_e32 v142, v20
	v_add_u32_e32 v20, 30, v35
	v_cvt_f32_u32_e32 v147, v21
	v_add_u32_e32 v21, 13, v35
	v_subrev_u32_e32 v25, 33, v35
	v_cvt_f32_i32_e32 v119, v27
	v_subrev_u32_e32 v27, 50, v35
	v_cvt_f32_u32_e32 v144, v20
	v_add_u32_e32 v20, 16, v35
	v_cvt_f32_u32_e32 v149, v21
	v_add_u32_e32 v21, -2, v35
	v_subrev_u32_e32 v23, 18, v35
	v_cvt_f32_i32_e32 v117, v25
	v_subrev_u32_e32 v25, 34, v35
	v_cvt_f32_i32_e32 v34, v27
	v_or_b32_e32 v27, 0xffffffc0, v222
	v_cvt_f32_u32_e32 v146, v20
	v_add_u32_e32 v20, 14, v35
	v_add_u32_e32 v17, v222, v17
	v_cvt_f32_i32_e32 v24, v21
	v_subrev_u32_e32 v21, 17, v35
	v_cvt_f32_i32_e32 v26, v23
	v_subrev_u32_e32 v23, 32, v35
	v_cvt_f32_i32_e32 v30, v25
	v_subrev_u32_e32 v25, 48, v35
	v_sub_u32_e32 v27, v27, v112
	v_cvt_f32_u32_e32 v148, v20
	v_cvt_f32_i32_e32 v20, v35
	v_cvt_f32_i32_e32 v113, v17
	v_add_u32_e32 v17, -3, v35
	v_cvt_f32_i32_e32 v115, v21
	v_subrev_u32_e32 v21, 19, v35
	v_cvt_f32_i32_e32 v28, v23
	v_subrev_u32_e32 v23, 35, v35
	v_cvt_f32_i32_e32 v32, v25
	v_subrev_u32_e32 v25, 51, v35
	v_cvt_f32_i32_e32 v226, v27
	v_add_u32_e32 v36, 0xffffffbf, v35
	v_add_u32_e32 v27, 0xffffffbe, v35
	v_add_u32_e32 v35, 0xffffffbd, v35
	v_or_b32_e32 v16, -16, v16
	v_cvt_f32_i32_e32 v23, v23
	v_cvt_f32_i32_e32 v27, v27
	v_cvt_f32_i32_e32 v36, v36
	v_cvt_f32_i32_e32 v227, v35
	v_sub_u32_e32 v16, v16, v112
	v_cvt_f32_i32_e32 v17, v17
	v_cvt_f32_i32_e32 v16, v16
	v_cvt_f32_i32_e32 v21, v21
	v_cvt_f32_i32_e32 v25, v25
	s_mov_b32 s0, 0xc2800000
	v_or_b32_e32 v35, s24, v31
	s_or_b32 s25, s24, 16
	v_cmp_le_f32_e64 s[50:51], s0, v226
	v_cmp_le_f32_e64 s[52:53], s0, v27
	v_cmp_le_f32_e64 s[54:55], s0, v36
	v_cmp_le_f32_e64 s[56:57], s0, v227
	v_mad_u64_u32 v[150:151], s[0:1], v35, s2, v[22:23]
	v_or_b32_e32 v35, s25, v222
	v_or_b32_e32 v31, s25, v31
	v_mul_lo_u32 v35, v35, s2
	v_mad_u64_u32 v[152:153], s[0:1], v31, s2, v[22:23]
	v_readlane_b32 s12, v253, 48
	v_add_u32_e32 v151, 0xd800, v150
	v_add_u32_e32 v153, 0xd800, v152
	v_or_b32_e32 v228, 32, v112
	v_or_b32_e32 v229, 48, v112
	v_or_b32_e32 v230, 0x50, v112
	v_or_b32_e32 v231, 0x60, v112
	v_or_b32_e32 v232, 0x70, v112
	v_or_b32_e32 v233, 0x80, v112
	v_or_b32_e32 v234, 16, v112
	v_lshl_add_u64 v[154:155], s[22:23], 0, v[128:129]
	v_lshl_add_u64 v[156:157], s[22:23], 0, v[18:19]
	v_mov_b32_e32 v122, v134
	v_mov_b32_e32 v120, v134
	s_add_i32 s26, s12, s21
	v_and_b32_e32 v158, 0x7fffffff, v20
	v_and_b32_e32 v161, 0x7fffffff, v17
	v_and_b32_e32 v160, 0x7fffffff, v24
	v_and_b32_e32 v162, 0x7fffffff, v16
	v_and_b32_e32 v165, 0x7fffffff, v21
	v_and_b32_e32 v164, 0x7fffffff, v26
	v_and_b32_e32 v166, 0x7fffffff, v28
	v_and_b32_e32 v169, 0x7fffffff, v23
	v_and_b32_e32 v168, 0x7fffffff, v30
	v_and_b32_e32 v170, 0x7fffffff, v32
	v_and_b32_e32 v173, 0x7fffffff, v25
	v_and_b32_e32 v172, 0x7fffffff, v34
	v_and_b32_e32 v175, 0x7fffffff, v27
	v_and_b32_e32 v174, 0x7fffffff, v36
	v_add_u32_e32 v235, v29, v33
	v_add_u32_e32 v236, v29, v35
	s_branch .LBB0_250
